# v13
# baseline (speedup 1.0000x reference)
.LBB0_121:
	v_add_u32_e32 v24, s33, v0
	v_ashrrev_i32_e32 v48, 4, v24
	v_and_b32_e32 v57, 63, v0
	v_and_b32_e32 v0, 0xfffff0, v48
	v_lshlrev_b32_e32 v5, 1, v48
	v_lshlrev_b32_e32 v4, 3, v24
	v_and_or_b32 v0, v5, 8, v0
	v_and_b32_e32 v182, 0x78, v4
	v_lshrrev_b32_e32 v5, 1, v48
	v_lshrrev_b32_e32 v0, 1, v0
	v_bfe_u32 v6, v4, 5, 2
	v_and_b32_e32 v7, 3, v48
	v_or_b32_e32 v0, v0, v6
	v_and_or_b32 v5, v5, 4, v7
	v_lshlrev_b32_e32 v180, 1, v182
	v_lshlrev_b32_e32 v0, 9, v0
	v_lshlrev_b32_e32 v5, 6, v5
	v_and_b32_e32 v7, 48, v180
	v_or3_b32 v25, v0, v5, v7
	v_add_u32_e32 v0, 32, v48
	v_and_b32_e32 v8, 0xfffff0, v0
	v_lshlrev_b32_e32 v9, 1, v0
	v_and_or_b32 v8, v9, 8, v8
	v_lshrrev_b32_e32 v8, 1, v8
	v_or_b32_e32 v6, v8, v6
	v_lshlrev_b32_e32 v6, 9, v6
	v_or3_b32 v26, v6, v5, v7
	v_lshlrev_b32_e32 v6, 4, v57
	v_lshlrev_b32_e32 v5, 3, v57
	v_and_b32_e32 v6, 0xc0, v6
	v_lshlrev_b32_e32 v7, 1, v57
	v_and_or_b32 v6, v5, 24, v6
	v_and_b32_e32 v7, 32, v7
	v_and_b32_e32 v5, 0x100, v5
	v_and_b32_e32 v188, 56, v4
	v_or3_b32 v58, v6, v7, v5
	v_and_b32_e32 v8, 0x70, v4
	global_load_dwordx4 v[4:7], v[2:3], off offset:256
	s_lshr_b32 s25, s27, 6
	s_lshl_b64 s[8:9], s[36:37], 12
	v_readlane_b32 s4, v255, 7
	s_add_u32 s6, s4, s8
	v_readlane_b32 s4, v255, 8
	s_addc_u32 s7, s4, s9
	s_lshl_b32 s4, s85, 8
	s_ashr_i32 s5, s4, 31
	s_lshl_b64 s[20:21], s[4:5], 1
	s_add_u32 s6, s6, s20
	s_addc_u32 s7, s7, s21
	s_add_u32 s4, s94, s20
	s_addc_u32 s5, s95, s21
	s_lshl_b64 s[10:11], s[36:37], 7
	v_readlane_b32 s22, v255, 5
	s_add_u32 s22, s22, s10
	v_readlane_b32 s23, v255, 6
	s_addc_u32 s23, s23, s11
	s_add_u32 s27, s4, 0x100
	s_addc_u32 s66, s5, 0
	s_cmp_lg_u32 0, -1
	s_cselect_b32 s67, 0, 0
	s_add_i32 s36, 0, 0x14800
	v_lshl_add_u32 v59, v1, 7, s36
	v_xad_u32 v1, v186, v8, v59
	v_or_b32_e32 v62, 32, v186
	v_or_b32_e32 v61, 64, v186
	v_or_b32_e32 v60, 0x60, v186
	v_ashrrev_i32_e32 v49, 31, v48
	v_lshlrev_b64 v[50:51], 12, v[48:49]
	v_ashrrev_i32_e32 v27, 3, v24
	v_lshlrev_b32_e32 v194, 6, v27
	v_ashrrev_i32_e32 v195, 31, v194
	v_lshl_add_u64 v[18:19], v[194:195], 1, s[22:23]
	v_lshlrev_b32_e32 v22, 1, v188
	v_mov_b32_e32 v23, v181
	v_lshl_add_u64 v[54:55], v[18:19], 0, v[22:23]
	v_add_u32_e32 v211, 0, v25
	v_lshlrev_b64 v[190:191], 11, v[48:49]
	s_add_i32 s22, 0, 0x10000
	v_add_u32_e32 v212, 0, v26
	v_lshlrev_b32_e32 v63, 8, v56
	v_lshlrev_b32_e32 v76, 7, v56
	s_movk_i32 s23, 0x70
	s_mov_b32 s36, s37
	s_mov_b32 s38, s37
	s_mov_b32 s39, s37
	s_mov_b32 s40, s37
	s_mov_b32 s41, s37
	s_mov_b32 s42, s37
	s_mov_b32 s43, s37
	s_mov_b32 s44, s37
	s_mov_b32 s45, s37
	s_mov_b32 s46, s37
	s_mov_b32 s47, s37
	s_mov_b32 s48, s37
	s_mov_b32 s49, s37
	s_mov_b32 s50, s37
	s_mov_b32 s51, s37
	v_add_u32_e32 v187, s67, v58
	v_lshl_add_u32 v236, v56, 2, s30
	v_mov_b32_e32 v237, 0
	v_mov_b32_e32 v241, 1.0
	s_waitcnt vmcnt(0)
	ds_write_b128 v1, v[4:7]
	global_load_dwordx4 v[4:7], v[2:3], off offset:288
	v_xad_u32 v1, v62, v8, v59
	s_waitcnt vmcnt(0)
	ds_write_b128 v1, v[4:7]
	global_load_dwordx4 v[4:7], v[2:3], off offset:320
	v_xad_u32 v1, v61, v8, v59
	s_waitcnt vmcnt(0)
	ds_write_b128 v1, v[4:7]
	global_load_dwordx4 v[2:5], v[2:3], off offset:352
	v_xad_u32 v1, v60, v8, v59
	s_waitcnt vmcnt(0)
	ds_write_b128 v1, v[2:5]
	v_lshl_add_u64 v[2:3], s[6:7], 0, v[50:51]
	v_lshl_add_u64 v[10:11], v[2:3], 0, v[180:181]
	global_load_dwordx4 v[2:5], v[10:11], off offset:256
	v_ashrrev_i32_e32 v1, 31, v0
	v_lshlrev_b64 v[52:53], 12, v[0:1]
	v_lshl_add_u64 v[6:7], s[6:7], 0, v[52:53]
	v_lshl_add_u64 v[14:15], v[6:7], 0, v[180:181]
	global_load_dwordx4 v[6:9], v[14:15], off offset:256
	s_nop 0
	global_load_dwordx4 v[10:13], v[10:11], off
	s_nop 0
	global_load_dwordx4 v[14:17], v[14:15], off
	v_lshlrev_b64 v[192:193], 11, v[0:1]
	global_load_dwordx4 v[18:21], v[54:55], off
	s_waitcnt vmcnt(0)
	v_lshlrev_b32_e32 v0, 8, v0
	v_lshlrev_b32_e32 v1, 8, v48
	s_waitcnt vmcnt(4)
	ds_write_b128 v211, v[2:5]
	v_and_b32_e32 v2, 0x70, v24
	v_bitop3_b32 v0, v180, v0, v2 bitop3:0xde
	v_add_u32_e32 v214, 0, v0
	v_lshlrev_b32_e32 v0, 7, v27
	v_bitop3_b32 v1, v180, v1, v2 bitop3:0xde
	v_bitop3_b32 v49, v22, v0, v2 bitop3:0xde
	v_add_u32_e32 v213, 0, v1
	v_add_u32_e32 v0, s22, v49
	s_waitcnt vmcnt(3)
	ds_write_b128 v212, v[6:9]
	s_waitcnt vmcnt(2)
	ds_write_b128 v213, v[10:13] offset:32768
	s_waitcnt vmcnt(1)
	ds_write_b128 v214, v[14:17] offset:32768
	s_waitcnt vmcnt(0)
	ds_write_b128 v0, v[18:21]
	v_lshlrev_b32_e32 v0, 4, v56
	v_and_b32_e32 v72, 0x70, v0
	v_bitop3_b32 v0, v186, v63, v72 bitop3:0xde
	v_add_u32_e32 v215, 0, v0
	s_waitcnt lgkmcnt(0)
	s_barrier
	ds_read_b128 v[16:19], v215 offset:32768
	ds_read_b128 v[20:23], v215 offset:40960
	s_waitcnt lgkmcnt(1)
	v_mfma_f32_32x32x16_bf16 v[32:47], v[16:19], v[128:131], 0
	v_bitop3_b32 v64, v62, v63, v72 bitop3:0xde
	v_add_u32_e32 v216, 0, v64
	ds_read_b128 v[64:67], v216 offset:32768
	ds_read_b128 v[68:71], v216 offset:40960
	v_mov_b64_e32 v[0:1], s[36:37]
	v_add_u32_e32 v238, 0, v49
	v_mov_b64_e32 v[14:15], s[50:51]
	v_add_u32_e32 v239, 0x12000, v238
	s_waitcnt lgkmcnt(2)
	v_mfma_f32_32x32x16_bf16 v[16:31], v[20:23], v[128:131], 0
	v_mov_b64_e32 v[2:3], s[38:39]
	v_mov_b64_e32 v[4:5], s[40:41]
	v_mov_b64_e32 v[6:7], s[42:43]
	v_mov_b64_e32 v[8:9], s[44:45]
	v_mov_b64_e32 v[10:11], s[46:47]
	v_mov_b64_e32 v[12:13], s[48:49]
	s_brev_b32 s50, 63
	s_waitcnt lgkmcnt(1)
	v_mfma_f32_32x32x16_bf16 v[32:47], v[64:67], v[132:135], v[32:47]
	v_bitop3_b32 v64, v61, v63, v72 bitop3:0xde
	v_add_u32_e32 v217, 0, v64
	s_mov_b32 s36, 2
	s_movk_i32 s51, 0x7ff
	s_waitcnt lgkmcnt(0)
	v_mfma_f32_32x32x16_bf16 v[16:31], v[68:71], v[132:135], v[16:31]
	ds_read_b128 v[64:67], v217 offset:32768
	ds_read_b128 v[68:71], v217 offset:40960
	s_waitcnt lgkmcnt(1)
	v_mfma_f32_32x32x16_bf16 v[32:47], v[64:67], v[136:139], v[32:47]
	v_bitop3_b32 v64, v60, v63, v72 bitop3:0xde
	v_add_u32_e32 v218, 0, v64
	s_waitcnt lgkmcnt(0)
	v_mfma_f32_32x32x16_bf16 v[16:31], v[68:71], v[136:139], v[16:31]
	ds_read_b128 v[64:67], v218 offset:32768
	ds_read_b128 v[68:71], v218 offset:40960
	s_waitcnt lgkmcnt(1)
	v_mfma_f32_32x32x16_bf16 v[32:47], v[64:67], v[140:143], v[32:47]
	v_or_b32_e32 v64, 0x80, v186
	v_bitop3_b32 v64, v64, v63, v72 bitop3:0xde
	v_add_u32_e32 v219, 0, v64
	s_waitcnt lgkmcnt(0)
	v_mfma_f32_32x32x16_bf16 v[16:31], v[68:71], v[140:143], v[16:31]
	ds_read_b128 v[64:67], v219 offset:32768
	ds_read_b128 v[68:71], v219 offset:40960
	s_waitcnt lgkmcnt(1)
	v_mfma_f32_32x32x16_bf16 v[32:47], v[64:67], v[144:147], v[32:47]
	v_or_b32_e32 v64, 0xa0, v186
	v_bitop3_b32 v64, v64, v63, v72 bitop3:0xde
	v_add_u32_e32 v220, 0, v64
	s_waitcnt lgkmcnt(0)
	v_mfma_f32_32x32x16_bf16 v[16:31], v[68:71], v[144:147], v[16:31]
	ds_read_b128 v[64:67], v220 offset:32768
	ds_read_b128 v[68:71], v220 offset:40960
	s_waitcnt lgkmcnt(1)
	v_mfma_f32_32x32x16_bf16 v[32:47], v[64:67], v[148:151], v[32:47]
	v_or_b32_e32 v64, 0xc0, v186
	v_bitop3_b32 v64, v64, v63, v72 bitop3:0xde
	v_add_u32_e32 v221, 0, v64
	s_waitcnt lgkmcnt(0)
	v_mfma_f32_32x32x16_bf16 v[16:31], v[68:71], v[148:151], v[16:31]
	ds_read_b128 v[64:67], v221 offset:32768
	ds_read_b128 v[68:71], v221 offset:40960
	s_waitcnt lgkmcnt(1)
	v_mfma_f32_32x32x16_bf16 v[32:47], v[64:67], v[152:155], v[32:47]
	v_or_b32_e32 v64, 0xe0, v186
	v_bitop3_b32 v63, v64, v63, v72 bitop3:0xde
	v_add_u32_e32 v222, 0, v63
	v_lshlrev_b32_e32 v63, 3, v56
	v_and_b32_e32 v77, 0x70, v63
	v_bitop3_b32 v63, v186, v63, s23 bitop3:0x78
	v_bitop3_b32 v223, v186, v76, v77 bitop3:0xde
	s_waitcnt lgkmcnt(0)
	v_mfma_f32_32x32x16_bf16 v[16:31], v[68:71], v[152:155], v[16:31]
	ds_read_b128 v[64:67], v222 offset:32768
	ds_read_b128 v[68:71], v222 offset:40960
	v_add_u32_e32 v224, s22, v223
	v_add_u32_e32 v225, v59, v63
	v_bitop3_b32 v226, v62, v76, v77 bitop3:0xde
	v_add_u32_e32 v227, s22, v226
	v_bitop3_b32 v229, v61, v76, v77 bitop3:0xde
	v_add_u32_e32 v230, s22, v229
	s_waitcnt lgkmcnt(1)
	v_mfma_f32_32x32x16_bf16 v[32:47], v[64:67], v[156:159], v[32:47]
	s_movk_i32 s23, 0x60
	v_bitop3_b32 v232, v60, v76, v77 bitop3:0xde
	v_add_u32_e32 v233, s22, v232
	s_add_u32 s22, s6, 0x40100
	s_waitcnt lgkmcnt(0)
	v_mfma_f32_32x32x16_bf16 v[16:31], v[68:71], v[156:159], v[16:31]
	ds_read_b128 v[64:67], v224
	ds_read_b128 v[68:71], v224 offset:4096
	ds_read_b128 v[72:75], v225
	s_waitcnt lgkmcnt(0)
	v_mfma_f32_32x32x16_bf16 v[32:47], v[64:67], v[72:75], v[32:47]
	v_mfma_f32_32x32x16_bf16 v[16:31], v[68:71], v[72:75], v[16:31]
	v_bitop3_b32 v70, v186, v77, 32 bitop3:0x36
	v_add_u32_e32 v228, v59, v70
	ds_read_b128 v[62:65], v227
	ds_read_b128 v[66:69], v227 offset:4096
	ds_read_b128 v[70:73], v228
	s_waitcnt lgkmcnt(0)
	v_mfma_f32_32x32x16_bf16 v[32:47], v[62:65], v[70:73], v[32:47]
	v_mfma_f32_32x32x16_bf16 v[16:31], v[66:69], v[70:73], v[16:31]
	v_bitop3_b32 v70, v186, v77, 64 bitop3:0x36
	v_add_u32_e32 v231, v59, v70
	ds_read_b128 v[62:65], v230
	ds_read_b128 v[66:69], v230 offset:4096
	ds_read_b128 v[70:73], v231
	s_waitcnt lgkmcnt(0)
	v_mfma_f32_32x32x16_bf16 v[32:47], v[62:65], v[70:73], v[32:47]
	v_mfma_f32_32x32x16_bf16 v[16:31], v[66:69], v[70:73], v[16:31]
	v_bitop3_b32 v68, v186, v77, s23 bitop3:0x36
	v_add_u32_e32 v234, v59, v68
	ds_read_b128 v[60:63], v233
	ds_read_b128 v[64:67], v233 offset:4096
	ds_read_b128 v[68:71], v234
	s_addc_u32 s23, s7, 0
	s_add_u32 s6, s6, 0x40000
	s_addc_u32 s7, s7, 0
	s_waitcnt lgkmcnt(0)
	v_mfma_f32_32x32x16_bf16 v[32:47], v[60:63], v[68:71], v[32:47]
	s_addk_i32 s67, 0x4000
	v_add_u32_e32 v240, s67, v58
	s_add_u32 s38, s8, s20
	s_addc_u32 s39, s9, s21
	s_sub_i32 s40, 0, s25
	s_nop 6
	v_max_f32_e32 v59, v33, v33
	v_max_f32_e32 v60, v32, v32
	v_mfma_f32_32x32x16_bf16 v[16:31], v[64:67], v[68:71], v[16:31]
	v_max_f32_e32 v59, v60, v59
	v_max3_f32 v59, v59, v34, v35
	v_max3_f32 v59, v59, v36, v37
	v_max3_f32 v59, v59, v38, v39
	v_max3_f32 v59, v59, v40, v41
	v_max3_f32 v59, v59, v42, v43
	v_max3_f32 v59, v59, v44, v45
	v_max3_f32 v59, v59, v46, v47
	s_nop 3
	v_max3_f32 v59, v59, v16, v17
	v_max3_f32 v59, v59, v18, v19
	v_max3_f32 v59, v59, v20, v21
	v_max3_f32 v59, v59, v22, v23
	v_max3_f32 v59, v59, v24, v25
	v_max3_f32 v59, v59, v26, v27
	v_max3_f32 v59, v59, v28, v29
	v_max3_f32 v59, v59, v30, v31
	v_mov_b32_e32 v60, v59
	s_nop 1
	v_permlane32_swap_b32_e32 v59, v60
	v_max_f32_e32 v60, v60, v60
	v_max_f32_e32 v59, v59, v59
	v_max_f32_e32 v235, v59, v60
	v_sub_f32_e32 v75, v21, v235
	v_sub_f32_e32 v74, v20, v235
	v_sub_f32_e32 v79, v17, v235
	v_sub_f32_e32 v78, v16, v235
	v_lshl_add_u64 v[16:17], s[22:23], 0, v[50:51]
	v_lshl_add_u64 v[20:21], s[22:23], 0, v[52:53]
	v_sub_f32_e32 v32, v32, v235
	v_lshl_add_u64 v[16:17], v[16:17], 0, v[180:181]
	v_lshl_add_u64 v[20:21], v[20:21], 0, v[180:181]
	v_sub_f32_e32 v33, v33, v235
	v_sub_f32_e32 v69, v27, v235
	v_sub_f32_e32 v68, v26, v235
	v_sub_f32_e32 v71, v25, v235
	v_sub_f32_e32 v70, v24, v235
	v_sub_f32_e32 v77, v19, v235
	v_sub_f32_e32 v76, v18, v235
	v_exp_f32_e32 v120, v32
	global_load_dwordx4 v[16:19], v[16:17], off
	v_add_co_u32_e32 v32, vcc, s68, v54
	global_load_dwordx4 v[24:27], v[20:21], off
	v_lshl_add_u64 v[20:21], s[6:7], 0, v[50:51]
	v_sub_f32_e32 v34, v34, v235
	v_sub_f32_e32 v35, v35, v235
	v_sub_f32_e32 v67, v29, v235
	v_sub_f32_e32 v66, v28, v235
	v_exp_f32_e32 v121, v33
	v_lshl_add_u64 v[20:21], v[20:21], 0, v[180:181]
	v_lshl_add_u64 v[28:29], s[6:7], 0, v[52:53]
	v_addc_co_u32_e32 v33, vcc, 0, v55, vcc
	v_sub_f32_e32 v73, v23, v235
	v_sub_f32_e32 v72, v22, v235
	v_exp_f32_e32 v122, v34
	v_exp_f32_e32 v124, v35
	global_load_dwordx4 v[20:23], v[20:21], off
	v_lshl_add_u64 v[28:29], v[28:29], 0, v[180:181]
	global_load_dwordx4 v[32:35], v[32:33], off
	v_sub_f32_e32 v65, v31, v235
	v_sub_f32_e32 v64, v30, v235
	global_load_dwordx4 v[28:31], v[28:29], off
	v_sub_f32_e32 v36, v36, v235
	v_sub_f32_e32 v37, v37, v235
	v_sub_f32_e32 v38, v38, v235
	v_sub_f32_e32 v39, v39, v235
	v_sub_f32_e32 v40, v40, v235
	v_sub_f32_e32 v41, v41, v235
	v_sub_f32_e32 v42, v42, v235
	v_sub_f32_e32 v43, v43, v235
	v_sub_f32_e32 v44, v44, v235
	v_sub_f32_e32 v45, v45, v235
	v_sub_f32_e32 v46, v46, v235
	v_sub_f32_e32 v47, v47, v235
	v_exp_f32_e32 v125, v36
	v_exp_f32_e32 v127, v37
	v_exp_f32_e32 v123, v38
	v_exp_f32_e32 v126, v39
	v_exp_f32_e32 v112, v40
	v_exp_f32_e32 v114, v41
	v_exp_f32_e32 v115, v42
	v_exp_f32_e32 v118, v43
	v_exp_f32_e32 v113, v44
	v_exp_f32_e32 v116, v45
	v_exp_f32_e32 v117, v46
	v_exp_f32_e32 v119, v47
	s_waitcnt vmcnt(0)
	s_waitcnt vmcnt(4)
	ds_write_b128 v211, v[16:19] offset:16384
	s_waitcnt vmcnt(3)
	ds_write_b128 v212, v[24:27] offset:16384
	s_waitcnt vmcnt(2)
	ds_write_b128 v213, v[20:23] offset:49152
	s_waitcnt vmcnt(0)
	ds_write_b128 v214, v[28:31] offset:49152
	v_lshlrev_b32_e32 v16, 11, v48
	v_and_b32_e32 v180, 0x7800, v16
	ds_write_b128 v239, v[32:35]
	v_cmp_gt_u32_e64 s[6:7], 32, v57
	v_mov_b64_e32 v[196:197], v[180:181]
	v_and_b32_e32 v180, 0x3c0, v194
	v_mov_b64_e32 v[62:63], v[14:15]
	v_mov_b64_e32 v[46:47], v[14:15]
	v_mov_b64_e32 v[30:31], v[14:15]
	v_mov_b64_e32 v[198:199], v[180:181]
	v_mov_b64_e32 v[60:61], v[12:13]
	v_mov_b64_e32 v[58:59], v[10:11]
	v_mov_b64_e32 v[56:57], v[8:9]
	v_mov_b64_e32 v[54:55], v[6:7]
	v_mov_b64_e32 v[52:53], v[4:5]
	v_mov_b64_e32 v[50:51], v[2:3]
	v_mov_b64_e32 v[48:49], v[0:1]
	v_mov_b64_e32 v[44:45], v[12:13]
	v_mov_b64_e32 v[42:43], v[10:11]
	v_mov_b64_e32 v[40:41], v[8:9]
	v_mov_b64_e32 v[38:39], v[6:7]
	v_mov_b64_e32 v[36:37], v[4:5]
	v_mov_b64_e32 v[34:35], v[2:3]
	v_mov_b64_e32 v[32:33], v[0:1]
	v_mov_b64_e32 v[28:29], v[12:13]
	v_mov_b64_e32 v[26:27], v[10:11]
	v_mov_b64_e32 v[24:25], v[8:9]
	v_mov_b64_e32 v[22:23], v[6:7]
	v_mov_b64_e32 v[20:21], v[4:5]
	v_mov_b64_e32 v[18:19], v[2:3]
	v_mov_b64_e32 v[16:17], v[0:1]
	s_waitcnt lgkmcnt(0)
	s_barrier
	v_lshlrev_b32_e32 v180, 1, v182
	v_lshlrev_b32_e32 v200, 1, v188
	v_mov_b32_e32 v201, v181
	v_lshl_add_u32 v190, v190, 1, v180
	v_lshl_add_u32 v192, v192, 1, v180
	v_lshl_add_u32 v194, v194, 1, v200
	v_lshl_add_u32 v196, v196, 1, v180
	v_lshl_add_u32 v198, v198, 1, v200
	s_mov_b32 s100, 0
	s_mov_b32 s101, 0x1c800

.Lmla_sl_merge:
	v_add_u32_e32 v240, s100, v187
	ds_read_b64_tr_b16 v[112:113], v240 offset:0
	ds_read_b64_tr_b16 v[114:115], v240 offset:0x800
	ds_read_b64_tr_b16 v[116:117], v240 offset:0x1000
	ds_read_b64_tr_b16 v[118:119], v240 offset:0x1800
	ds_read_b64_tr_b16 v[120:121], v240 offset:0x2000
	ds_read_b64_tr_b16 v[122:123], v240 offset:0x2800
	ds_read_b64_tr_b16 v[124:125], v240 offset:0x3000
	ds_read_b64_tr_b16 v[126:127], v240 offset:0x3800
	s_nop 0
	s_waitcnt lgkmcnt(4)
	v_mfma_f32_32x32x16_bf16 v[16:31], v[64:67], v[112:115], v[16:31]
	ds_read_b64_tr_b16 v[112:113], v240 offset:0x200
	ds_read_b64_tr_b16 v[114:115], v240 offset:0xa00
	v_mfma_f32_32x32x16_bf16 v[16:31], v[68:71], v[116:119], v[16:31]
	ds_read_b64_tr_b16 v[116:117], v240 offset:0x1200
	ds_read_b64_tr_b16 v[118:119], v240 offset:0x1a00
	s_waitcnt lgkmcnt(4)
	v_mfma_f32_32x32x16_bf16 v[16:31], v[72:75], v[120:123], v[16:31]
	ds_read_b64_tr_b16 v[120:121], v240 offset:0x2200
	ds_read_b64_tr_b16 v[122:123], v240 offset:0x2a00
	v_mfma_f32_32x32x16_bf16 v[16:31], v[76:79], v[124:127], v[16:31]
	ds_read_b64_tr_b16 v[124:125], v240 offset:0x3200
	ds_read_b64_tr_b16 v[126:127], v240 offset:0x3a00
	s_waitcnt lgkmcnt(4)
	v_mfma_f32_32x32x16_bf16 v[32:47], v[64:67], v[112:115], v[32:47]
	ds_read_b64_tr_b16 v[112:113], v240 offset:0x400
	ds_read_b64_tr_b16 v[114:115], v240 offset:0xc00
	v_mfma_f32_32x32x16_bf16 v[32:47], v[68:71], v[116:119], v[32:47]
	ds_read_b64_tr_b16 v[116:117], v240 offset:0x1400
	ds_read_b64_tr_b16 v[118:119], v240 offset:0x1c00
	s_waitcnt lgkmcnt(4)
	v_mfma_f32_32x32x16_bf16 v[32:47], v[72:75], v[120:123], v[32:47]
	ds_read_b64_tr_b16 v[120:121], v240 offset:0x2400
	ds_read_b64_tr_b16 v[122:123], v240 offset:0x2c00
	v_mfma_f32_32x32x16_bf16 v[32:47], v[76:79], v[124:127], v[32:47]
	ds_read_b64_tr_b16 v[124:125], v240 offset:0x3400
	ds_read_b64_tr_b16 v[126:127], v240 offset:0x3c00
	s_waitcnt lgkmcnt(4)
	v_mfma_f32_32x32x16_bf16 v[48:63], v[64:67], v[112:115], v[48:63]
	ds_read_b64_tr_b16 v[112:113], v240 offset:0x600
	ds_read_b64_tr_b16 v[114:115], v240 offset:0xe00
	v_mfma_f32_32x32x16_bf16 v[48:63], v[68:71], v[116:119], v[48:63]
	ds_read_b64_tr_b16 v[116:117], v240 offset:0x1600
	ds_read_b64_tr_b16 v[118:119], v240 offset:0x1e00
	s_waitcnt lgkmcnt(4)
	v_mfma_f32_32x32x16_bf16 v[48:63], v[72:75], v[120:123], v[48:63]
	ds_read_b64_tr_b16 v[120:121], v240 offset:0x2600
	ds_read_b64_tr_b16 v[122:123], v240 offset:0x2e00
	v_mfma_f32_32x32x16_bf16 v[48:63], v[76:79], v[124:127], v[48:63]
	ds_read_b64_tr_b16 v[124:125], v240 offset:0x3600
	ds_read_b64_tr_b16 v[126:127], v240 offset:0x3e00
	s_waitcnt lgkmcnt(4)
	v_mfma_f32_32x32x16_bf16 v[0:15], v[64:67], v[112:115], v[0:15]
	v_max_f32_e32 v64, v97, v97
	v_max_f32_e32 v65, v96, v96
	v_max_f32_e32 v64, v65, v64
	v_max3_f32 v64, v64, v98, v99
	v_max3_f32 v64, v64, v100, v101
	v_max3_f32 v64, v64, v102, v103
	v_max3_f32 v64, v64, v104, v105
	v_mfma_f32_32x32x16_bf16 v[0:15], v[68:71], v[116:119], v[0:15]
	v_max3_f32 v64, v64, v106, v107
	v_max3_f32 v64, v64, v108, v109
	v_max3_f32 v64, v64, v110, v111
	v_max3_f32 v64, v64, v80, v81
	v_max3_f32 v64, v64, v82, v83
	v_max3_f32 v64, v64, v84, v85
	v_max3_f32 v64, v64, v86, v87
	s_waitcnt lgkmcnt(0)
	v_mfma_f32_32x32x16_bf16 v[0:15], v[72:75], v[120:123], v[0:15]
	v_max3_f32 v64, v64, v88, v89
	v_max3_f32 v64, v64, v90, v91
	v_max3_f32 v64, v64, v92, v93
	v_max3_f32 v64, v64, v94, v95
	v_mov_b32_e32 v65, v64
	s_nop 1
	v_permlane32_swap_b32_e32 v64, v65
	v_mfma_f32_32x32x16_bf16 v[0:15], v[76:79], v[124:127], v[0:15]
	v_max_f32_e32 v65, v65, v65
	v_max_f32_e32 v64, v64, v64
	v_max_f32_e32 v64, v64, v65
	v_cmp_ge_f32_e32 vcc, s63, v64
	s_cmp_eq_u64 vcc, exec
	v_mov_b32_e32 v244, 1.0
	s_cbranch_scc0 .LBB0_140
.LBB0_125:
	s_waitcnt vmcnt(0)
	v_add_u32_e32 v64, 0x10000, v238
	v_cmp_gt_f32_e32 vcc, 1.0, v244
	v_add_u32_e32 v65, s101, v211
	v_add_u32_e32 v66, s101, v212
	ds_write_b128 v65, v[160:163]
	ds_write_b128 v66, v[164:167]
	ds_write_b128 v213, v[168:171] offset:32768
	ds_write_b128 v214, v[172:175] offset:32768
	ds_write_b128 v64, v[176:179]
	s_cbranch_vccz .LBB0_129
	s_and_saveexec_b64 s[22:23], s[6:7]
	ds_write_b32 v236, v244 offset:128
	s_or_b64 exec, exec, s[22:23]
	s_waitcnt lgkmcnt(0)
	v_add_u32_e32 v76, s30, v186
	ds_read_b128 v[64:67], v76 offset:224
	ds_read_b128 v[68:71], v76 offset:192
	ds_read_b128 v[72:75], v76 offset:160
	ds_read_b128 v[76:79], v76 offset:128
	s_waitcnt lgkmcnt(3)
	v_pk_mul_f32 v[28:29], v[28:29], v[64:65]
	s_waitcnt lgkmcnt(2)
	v_pk_mul_f32 v[24:25], v[24:25], v[68:69]
	s_waitcnt lgkmcnt(1)
	v_pk_mul_f32 v[20:21], v[20:21], v[72:73]
	v_pk_mul_f32 v[30:31], v[30:31], v[66:67]
	v_pk_mul_f32 v[26:27], v[26:27], v[70:71]
	v_pk_mul_f32 v[22:23], v[22:23], v[74:75]
	s_waitcnt lgkmcnt(0)
	v_pk_mul_f32 v[18:19], v[18:19], v[78:79]
	v_pk_mul_f32 v[16:17], v[16:17], v[76:77]
	v_pk_mul_f32 v[44:45], v[44:45], v[64:65]
	v_pk_mul_f32 v[40:41], v[40:41], v[68:69]
	v_pk_mul_f32 v[36:37], v[36:37], v[72:73]
	v_pk_mul_f32 v[46:47], v[46:47], v[66:67]
	v_pk_mul_f32 v[42:43], v[42:43], v[70:71]
	v_pk_mul_f32 v[38:39], v[38:39], v[74:75]
	v_pk_mul_f32 v[34:35], v[34:35], v[78:79]
	v_pk_mul_f32 v[32:33], v[32:33], v[76:77]
	v_pk_mul_f32 v[60:61], v[60:61], v[64:65]
	v_pk_mul_f32 v[56:57], v[56:57], v[68:69]
	v_pk_mul_f32 v[52:53], v[52:53], v[72:73]
	v_pk_mul_f32 v[62:63], v[62:63], v[66:67]
	v_pk_mul_f32 v[58:59], v[58:59], v[70:71]
	v_pk_mul_f32 v[54:55], v[54:55], v[74:75]
	v_pk_mul_f32 v[50:51], v[50:51], v[78:79]
	v_pk_mul_f32 v[48:49], v[48:49], v[76:77]
	v_pk_mul_f32 v[12:13], v[12:13], v[64:65]
	v_pk_mul_f32 v[8:9], v[8:9], v[68:69]
	v_pk_mul_f32 v[4:5], v[4:5], v[72:73]
	v_pk_mul_f32 v[14:15], v[14:15], v[66:67]
	v_pk_mul_f32 v[10:11], v[10:11], v[70:71]
	v_pk_mul_f32 v[6:7], v[6:7], v[74:75]
	v_pk_mul_f32 v[2:3], v[2:3], v[78:79]
	v_pk_mul_f32 v[0:1], v[0:1], v[76:77]
.LBB0_129:
	v_exp_f32_e32 v73, v96
	v_exp_f32_e32 v75, v97
	v_exp_f32_e32 v76, v98
	v_exp_f32_e32 v77, v99
	v_exp_f32_e32 v78, v100
	v_exp_f32_e32 v79, v101
	v_exp_f32_e32 v72, v102
	v_exp_f32_e32 v74, v103
	v_exp_f32_e32 v66, v104
	v_exp_f32_e32 v67, v105
	v_exp_f32_e32 v68, v106
	v_exp_f32_e32 v69, v110
	v_exp_f32_e32 v71, v107
	v_exp_f32_e32 v64, v108
	v_exp_f32_e32 v65, v109
	v_exp_f32_e32 v70, v111
	s_sub_i32 s44, 0x20800, s100
	s_sub_i32 s44, s44, s101
	s_mov_b32 s101, s100
	s_mov_b32 s100, s44
	s_waitcnt lgkmcnt(0)
	s_barrier
	ds_read_b128 v[246:249], v215 offset:32768
	ds_read_b128 v[250:253], v215 offset:40960
	v_xor_b32_e32 v112, 0x80000000, v235
	v_mov_b32_e32 v113, v112
	v_mov_b32_e32 v114, v112
	v_mov_b32_e32 v115, v112
	v_mov_b32_e32 v116, v112
	v_mov_b32_e32 v117, v112
	v_mov_b32_e32 v118, v112
	v_mov_b32_e32 v119, v112
	v_mov_b32_e32 v120, v112
	v_mov_b32_e32 v121, v112
	v_mov_b32_e32 v122, v112
	v_mov_b32_e32 v123, v112
	v_mov_b32_e32 v124, v112
	v_mov_b32_e32 v125, v112
	v_mov_b32_e32 v126, v112
	v_mov_b32_e32 v127, v112
	v_exp_f32_e32 v189, v80
	v_add_f32_e32 v80, 0, v73
	s_waitcnt lgkmcnt(1)
	v_mfma_f32_32x32x16_bf16 v[96:111], v[246:249], v[128:131], v[112:127]
	v_add_f32_e32 v80, v75, v80
	v_add_f32_e32 v80, v76, v80
	v_add_f32_e32 v80, v77, v80
	v_add_f32_e32 v80, v78, v80
	v_add_f32_e32 v80, v79, v80
	v_add_f32_e32 v80, v72, v80
	v_add_f32_e32 v80, v74, v80
	s_waitcnt lgkmcnt(0)
	v_mfma_f32_32x32x16_bf16 v[112:127], v[250:253], v[128:131], v[112:127]
	ds_read_b128 v[246:249], v216 offset:32768
	ds_read_b128 v[250:253], v216 offset:40960
	v_add_f32_e32 v80, v66, v80
	v_add_f32_e32 v80, v67, v80
	v_add_f32_e32 v80, v68, v80
	v_add_f32_e32 v80, v71, v80
	v_add_f32_e32 v80, v64, v80
	v_exp_f32_e32 v201, v81
	s_waitcnt lgkmcnt(1)
	v_mfma_f32_32x32x16_bf16 v[96:111], v[246:249], v[132:135], v[96:111]
	v_add_f32_e32 v80, v65, v80
	v_add_f32_e32 v80, v69, v80
	v_add_f32_e32 v80, v70, v80
	v_exp_f32_e32 v84, v84
	v_add_f32_e32 v80, v189, v80
	v_exp_f32_e32 v85, v85
	v_add_f32_e32 v80, v201, v80
	s_waitcnt lgkmcnt(0)
	v_mfma_f32_32x32x16_bf16 v[112:127], v[250:253], v[132:135], v[112:127]
	ds_read_b128 v[246:249], v217 offset:32768
	ds_read_b128 v[250:253], v217 offset:40960
	v_exp_f32_e32 v86, v86
	v_exp_f32_e32 v87, v87
	v_exp_f32_e32 v90, v90
	v_exp_f32_e32 v91, v91
	v_exp_f32_e32 v92, v92
	v_exp_f32_e32 v93, v93
	s_waitcnt lgkmcnt(1)
	v_mfma_f32_32x32x16_bf16 v[96:111], v[246:249], v[136:139], v[96:111]
	v_exp_f32_e32 v94, v94
	v_exp_f32_e32 v95, v95
	v_cvt_pk_bf16_f32 v81, v76, v77
	v_cvt_pk_bf16_f32 v66, v66, v67
	v_cvt_pk_bf16_f32 v67, v68, v71
	v_cvt_pk_bf16_f32 v68, v64, v65
	v_cvt_pk_bf16_f32 v69, v69, v70
	s_waitcnt lgkmcnt(0)
	v_mfma_f32_32x32x16_bf16 v[112:127], v[250:253], v[136:139], v[112:127]
	ds_read_b128 v[246:249], v218 offset:32768
	ds_read_b128 v[250:253], v218 offset:40960
	v_cvt_pk_bf16_f32 v77, v90, v91
	v_permlane32_swap_b32_e32 v66, v68
	v_permlane32_swap_b32_e32 v67, v69
	s_waitcnt lgkmcnt(1)
	v_mfma_f32_32x32x16_bf16 v[96:111], v[246:249], v[140:143], v[96:111]
	s_waitcnt lgkmcnt(0)
	v_mfma_f32_32x32x16_bf16 v[112:127], v[250:253], v[140:143], v[112:127]
	ds_read_b128 v[246:249], v219 offset:32768
	ds_read_b128 v[250:253], v219 offset:40960
	s_waitcnt lgkmcnt(1)
	v_mfma_f32_32x32x16_bf16 v[96:111], v[246:249], v[144:147], v[96:111]
	ds_read_b128 v[246:249], v220 offset:32768
	s_waitcnt lgkmcnt(1)
	v_mfma_f32_32x32x16_bf16 v[112:127], v[250:253], v[144:147], v[112:127]
	ds_read_b128 v[250:253], v220 offset:40960
	s_waitcnt lgkmcnt(1)
	v_mfma_f32_32x32x16_bf16 v[96:111], v[246:249], v[148:151], v[96:111]
	ds_read_b128 v[246:249], v221 offset:32768
	s_waitcnt lgkmcnt(1)
	v_mfma_f32_32x32x16_bf16 v[112:127], v[250:253], v[148:151], v[112:127]
	ds_read_b128 v[250:253], v221 offset:40960
	s_waitcnt lgkmcnt(1)
	v_mfma_f32_32x32x16_bf16 v[96:111], v[246:249], v[152:155], v[96:111]
	ds_read_b128 v[246:249], v222 offset:32768
	s_waitcnt lgkmcnt(1)
	v_mfma_f32_32x32x16_bf16 v[112:127], v[250:253], v[152:155], v[112:127]
	ds_read_b128 v[250:253], v222 offset:40960
	ds_read_b128 v[160:163], v224
	ds_read_b128 v[164:167], v224 offset:4096
	ds_read_b128 v[206:209], v225
	s_waitcnt lgkmcnt(4)
	v_mfma_f32_32x32x16_bf16 v[96:111], v[246:249], v[156:159], v[96:111]
	ds_read_b128 v[246:249], v227
	s_waitcnt lgkmcnt(4)
	v_mfma_f32_32x32x16_bf16 v[112:127], v[250:253], v[156:159], v[112:127]
	ds_read_b128 v[250:253], v227 offset:4096
	s_waitcnt lgkmcnt(2)
	v_mfma_f32_32x32x16_bf16 v[96:111], v[160:163], v[206:209], v[96:111]
	v_mfma_f32_32x32x16_bf16 v[112:127], v[164:167], v[206:209], v[112:127]
	ds_read_b128 v[160:163], v228
	ds_read_b128 v[164:167], v230
	ds_read_b128 v[206:209], v230 offset:4096
	s_waitcnt lgkmcnt(2)
	v_mfma_f32_32x32x16_bf16 v[96:111], v[246:249], v[160:163], v[96:111]
	v_mfma_f32_32x32x16_bf16 v[112:127], v[250:253], v[160:163], v[112:127]
	ds_read_b128 v[246:249], v231
	ds_read_b128 v[250:253], v233
	ds_read_b128 v[160:163], v233 offset:4096
	s_waitcnt lgkmcnt(2)
	v_mfma_f32_32x32x16_bf16 v[96:111], v[164:167], v[246:249], v[96:111]
	v_mfma_f32_32x32x16_bf16 v[112:127], v[206:209], v[246:249], v[112:127]
	ds_read_b128 v[164:167], v234
	s_waitcnt lgkmcnt(0)
	v_mfma_f32_32x32x16_bf16 v[96:111], v[250:253], v[164:167], v[96:111]
	v_exp_f32_e32 v206, v82
	v_exp_f32_e32 v207, v83
	v_exp_f32_e32 v208, v88
	v_exp_f32_e32 v209, v89
	v_add_f32_e32 v80, v206, v80
	v_add_f32_e32 v80, v207, v80
	v_add_f32_e32 v80, v84, v80
	v_add_f32_e32 v80, v85, v80
	v_add_f32_e32 v80, v86, v80
	v_add_f32_e32 v80, v87, v80
	v_add_f32_e32 v80, v208, v80
	v_add_f32_e32 v80, v209, v80
	v_mfma_f32_32x32x16_bf16 v[112:127], v[160:163], v[164:167], v[112:127]
	v_add_f32_e32 v80, v90, v80
	v_add_f32_e32 v80, v91, v80
	v_add_f32_e32 v80, v92, v80
	v_add_f32_e32 v80, v93, v80
	v_add_f32_e32 v80, v94, v80
	v_add_f32_e32 v88, v95, v80
	v_mov_b32_e32 v89, v88
	v_cvt_pk_bf16_f32 v80, v73, v75
	v_cvt_pk_bf16_f32 v82, v78, v79
	v_cvt_pk_bf16_f32 v83, v72, v74
	v_cvt_pk_bf16_f32 v72, v189, v201
	v_cvt_pk_bf16_f32 v73, v206, v207
	v_cvt_pk_bf16_f32 v74, v84, v85
	v_cvt_pk_bf16_f32 v75, v86, v87
	v_cvt_pk_bf16_f32 v76, v208, v209
	v_cvt_pk_bf16_f32 v78, v92, v93
	v_cvt_pk_bf16_f32 v79, v94, v95
	v_permlane32_swap_b32_e32 v88, v89
	v_permlane32_swap_b32_e32 v80, v82
	v_permlane32_swap_b32_e32 v81, v83
	v_permlane32_swap_b32_e32 v72, v74
	v_permlane32_swap_b32_e32 v73, v75
	v_permlane32_swap_b32_e32 v76, v78
	v_permlane32_swap_b32_e32 v77, v79
	s_add_i32 s43, s36, 1
	s_cmp_le_u32 s43, s25
	s_cselect_b64 s[22:23], -1, 0
	s_cmp_gt_u32 s43, s25
	s_cbranch_scc1 .LBB0_131
	s_add_u32 s44, s41, 0x6502400
	s_addc_u32 s45, s42, 0
	s_add_u32 s46, s41, 0x6502500
	s_addc_u32 s47, s42, 0
	global_load_dwordx4 v[160:163], v190, s[46:47]
	global_load_dwordx4 v[164:167], v192, s[46:47]
	global_load_dwordx4 v[168:171], v190, s[44:45]
	global_load_dwordx4 v[172:175], v192, s[44:45]
	s_add_u32 s44, s20, 0x28f28400
	s_addc_u32 s45, s21, 0
	global_load_dwordx4 v[176:179], v194, s[44:45]
.LBB0_131:
	v_add_u32_e32 v240, s100, v187
	ds_read_b64_tr_b16 v[84:85], v240 offset:0
	ds_read_b64_tr_b16 v[86:87], v240 offset:0x800
	ds_read_b64_tr_b16 v[90:91], v240 offset:0x1000
	ds_read_b64_tr_b16 v[92:93], v240 offset:0x1800
	ds_read_b64_tr_b16 v[206:207], v240 offset:0x2000
	ds_read_b64_tr_b16 v[208:209], v240 offset:0x2800
	ds_read_b64_tr_b16 v[246:247], v240 offset:0x3000
	ds_read_b64_tr_b16 v[248:249], v240 offset:0x3800
	s_nop 0
	s_waitcnt lgkmcnt(4)
	v_mfma_f32_32x32x16_bf16 v[16:31], v[80:83], v[84:87], v[16:31]
	ds_read_b64_tr_b16 v[84:85], v240 offset:0x200
	ds_read_b64_tr_b16 v[86:87], v240 offset:0xa00
	v_mfma_f32_32x32x16_bf16 v[16:31], v[66:69], v[90:93], v[16:31]
	ds_read_b64_tr_b16 v[90:91], v240 offset:0x1200
	ds_read_b64_tr_b16 v[92:93], v240 offset:0x1a00
	s_waitcnt lgkmcnt(4)
	v_mfma_f32_32x32x16_bf16 v[16:31], v[72:75], v[206:209], v[16:31]
	ds_read_b64_tr_b16 v[206:207], v240 offset:0x2200
	ds_read_b64_tr_b16 v[208:209], v240 offset:0x2a00
	v_mfma_f32_32x32x16_bf16 v[16:31], v[76:79], v[246:249], v[16:31]
	ds_read_b64_tr_b16 v[246:247], v240 offset:0x3200
	ds_read_b64_tr_b16 v[248:249], v240 offset:0x3a00
	s_waitcnt lgkmcnt(4)
	v_mfma_f32_32x32x16_bf16 v[32:47], v[80:83], v[84:87], v[32:47]
	ds_read_b64_tr_b16 v[84:85], v240 offset:0x400
	ds_read_b64_tr_b16 v[86:87], v240 offset:0xc00
	v_mfma_f32_32x32x16_bf16 v[32:47], v[66:69], v[90:93], v[32:47]
	ds_read_b64_tr_b16 v[90:91], v240 offset:0x1400
	ds_read_b64_tr_b16 v[92:93], v240 offset:0x1c00
	s_waitcnt lgkmcnt(4)
	v_mfma_f32_32x32x16_bf16 v[32:47], v[72:75], v[206:209], v[32:47]
	ds_read_b64_tr_b16 v[206:207], v240 offset:0x2400
	ds_read_b64_tr_b16 v[208:209], v240 offset:0x2c00
	v_mfma_f32_32x32x16_bf16 v[32:47], v[76:79], v[246:249], v[32:47]
	ds_read_b64_tr_b16 v[246:247], v240 offset:0x3400
	ds_read_b64_tr_b16 v[248:249], v240 offset:0x3c00
	s_waitcnt lgkmcnt(4)
	v_mfma_f32_32x32x16_bf16 v[48:63], v[80:83], v[84:87], v[48:63]
	ds_read_b64_tr_b16 v[84:85], v240 offset:0x600
	ds_read_b64_tr_b16 v[86:87], v240 offset:0xe00
	v_mfma_f32_32x32x16_bf16 v[48:63], v[66:69], v[90:93], v[48:63]
	ds_read_b64_tr_b16 v[90:91], v240 offset:0x1600
	ds_read_b64_tr_b16 v[92:93], v240 offset:0x1e00
	s_waitcnt lgkmcnt(4)
	v_mfma_f32_32x32x16_bf16 v[48:63], v[72:75], v[206:209], v[48:63]
	ds_read_b64_tr_b16 v[206:207], v240 offset:0x2600
	ds_read_b64_tr_b16 v[208:209], v240 offset:0x2e00
	v_mfma_f32_32x32x16_bf16 v[48:63], v[76:79], v[246:249], v[48:63]
	ds_read_b64_tr_b16 v[246:247], v240 offset:0x3600
	ds_read_b64_tr_b16 v[248:249], v240 offset:0x3e00
	s_waitcnt lgkmcnt(4)
	v_mfma_f32_32x32x16_bf16 v[0:15], v[80:83], v[84:87], v[0:15]
	v_max_f32_e32 v80, v97, v97
	v_max_f32_e32 v81, v96, v96
	v_cndmask_b32_e64 v87, v105, v204, s[8:9]
	v_cndmask_b32_e64 v86, v104, v204, s[8:9]
	v_cndmask_b32_e64 v85, v107, v204, s[8:9]
	v_cndmask_b32_e64 v84, v106, v204, s[8:9]
	v_cndmask_b32_e64 v83, v109, v204, s[8:9]
	v_mfma_f32_32x32x16_bf16 v[0:15], v[66:69], v[90:93], v[0:15]
	v_max_f32_e32 v90, v81, v80
	v_max3_f32 v90, v90, v98, v99
	v_max3_f32 v90, v90, v100, v101
	v_max3_f32 v90, v90, v102, v103
	v_max3_f32 v90, v90, v86, v87
	v_cndmask_b32_e64 v82, v108, v204, s[8:9]
	v_max3_f32 v90, v90, v84, v85
	s_waitcnt lgkmcnt(0)
	v_mfma_f32_32x32x16_bf16 v[0:15], v[72:75], v[206:209], v[0:15]
	v_cndmask_b32_e64 v81, v111, v204, s[8:9]
	v_cndmask_b32_e64 v80, v110, v204, s[8:9]
	v_max3_f32 v90, v90, v82, v83
	v_max3_f32 v90, v90, v80, v81
	v_cndmask_b32_e64 v75, v117, v204, s[8:9]
	v_cndmask_b32_e64 v74, v116, v204, s[8:9]
	v_cndmask_b32_e64 v73, v119, v204, s[8:9]
	v_mfma_f32_32x32x16_bf16 v[0:15], v[76:79], v[246:249], v[0:15]
	v_cndmask_b32_e64 v79, v113, v204, s[8:9]
	v_cndmask_b32_e64 v78, v112, v204, s[8:9]
	v_cndmask_b32_e64 v77, v115, v204, s[8:9]
	v_cndmask_b32_e64 v76, v114, v204, s[8:9]
	v_max3_f32 v90, v90, v78, v79
	v_max3_f32 v90, v90, v76, v77
	v_cndmask_b32_e64 v72, v118, v204, s[8:9]
	v_max3_f32 v90, v90, v74, v75
	v_cndmask_b32_e64 v71, v121, v204, s[8:9]
	v_cndmask_b32_e64 v70, v120, v204, s[8:9]
	v_max3_f32 v90, v90, v72, v73
	v_cndmask_b32_e64 v69, v123, v204, s[8:9]
	v_cndmask_b32_e64 v68, v122, v204, s[8:9]
	v_max3_f32 v90, v90, v70, v71
	v_cndmask_b32_e64 v67, v125, v204, s[8:9]
	v_cndmask_b32_e64 v66, v124, v204, s[8:9]
	v_max3_f32 v90, v90, v68, v69
	v_cndmask_b32_e64 v65, v127, v204, s[8:9]
	v_cndmask_b32_e64 v64, v126, v204, s[8:9]
	v_max3_f32 v90, v90, v66, v67
	v_max3_f32 v90, v90, v64, v65
	v_mov_b32_e32 v91, v90
	s_nop 1
	v_permlane32_swap_b32_e32 v90, v91
	v_max_f32_e32 v91, v91, v91
	v_max_f32_e32 v90, v90, v90
	v_max_f32_e32 v91, v90, v91
	v_cmp_ge_f32_e32 vcc, s63, v91
	s_cmp_eq_u64 vcc, exec
	v_mov_b32_e32 v90, 1.0
	s_cbranch_scc0 .LBB0_141
.LBB0_132:
	s_waitcnt vmcnt(0)
	s_andn2_b64 vcc, exec, s[22:23]
	s_cbranch_vccnz .LBB0_134
	v_add_u32_e32 v92, s101, v211
	v_add_u32_e32 v93, s101, v212
	ds_write_b128 v92, v[160:163]
	ds_write_b128 v93, v[164:167]
	ds_write_b128 v213, v[168:171] offset:49152
	ds_write_b128 v214, v[172:175] offset:49152
	ds_write_b128 v239, v[176:179]

.LBB0_138:
	s_add_u32 s10, s10, 0x4000
	v_exp_f32_e32 v120, v96
	v_exp_f32_e32 v121, v97
	v_exp_f32_e32 v122, v98
	v_exp_f32_e32 v124, v99
	v_exp_f32_e32 v125, v100
	v_exp_f32_e32 v127, v101
	v_exp_f32_e32 v123, v102
	v_exp_f32_e32 v126, v103
	v_exp_f32_e32 v112, v86
	v_exp_f32_e32 v114, v87
	v_exp_f32_e32 v115, v84
	v_exp_f32_e32 v118, v85
	v_exp_f32_e32 v113, v82
	v_exp_f32_e32 v116, v83
	v_exp_f32_e32 v117, v80
	v_exp_f32_e32 v119, v81
	s_addc_u32 s11, s11, 0
	v_add_f32_e32 v80, v242, v243
	s_add_u32 s38, s38, 0x80000
	v_fmac_f32_e32 v80, v241, v237
	v_add_f32_e32 v237, v88, v89
	s_addc_u32 s39, s39, 0
	s_sub_i32 s44, 0x20800, s100
	s_sub_i32 s44, s44, s101
	s_mov_b32 s101, s100
	s_mov_b32 s100, s44
	s_add_i32 s36, s36, 2
	v_fmac_f32_e32 v237, v80, v244
	s_cmp_gt_u32 s36, s25
	s_waitcnt lgkmcnt(0)
	s_barrier
	s_cbranch_scc1 .LBB0_142
	v_mov_b32_e32 v241, v90
	s_branch .LBB0_122

.LBB0_142:
	v_add_u32_e32 v187, s100, v187
	v_exp_f32_e32 v91, v64
	v_add_f32_e32 v64, 0, v120
	v_add_f32_e32 v64, v121, v64
	v_add_f32_e32 v64, v122, v64
	v_add_f32_e32 v64, v124, v64
	v_add_f32_e32 v64, v125, v64
	v_add_f32_e32 v64, v127, v64
	v_add_f32_e32 v64, v123, v64
	v_add_f32_e32 v64, v126, v64
	v_add_f32_e32 v64, v112, v64
	v_add_f32_e32 v64, v114, v64
	v_add_f32_e32 v64, v115, v64
	v_add_f32_e32 v64, v118, v64
	v_exp_f32_e32 v78, v78
	v_add_f32_e32 v64, v113, v64
	v_exp_f32_e32 v79, v79
	v_add_f32_e32 v64, v116, v64
	v_exp_f32_e32 v76, v76
	v_add_f32_e32 v64, v117, v64
	v_exp_f32_e32 v77, v77
	v_add_f32_e32 v64, v119, v64
	v_exp_f32_e32 v80, v74
	v_add_f32_e32 v64, v78, v64
	v_exp_f32_e32 v81, v75
	v_add_f32_e32 v64, v79, v64
	v_exp_f32_e32 v82, v72
	v_add_f32_e32 v64, v76, v64
	v_exp_f32_e32 v83, v73
	v_add_f32_e32 v64, v77, v64
	v_exp_f32_e32 v84, v70
	v_add_f32_e32 v64, v80, v64
	v_exp_f32_e32 v85, v71
	v_add_f32_e32 v64, v81, v64
	v_exp_f32_e32 v86, v68
	v_add_f32_e32 v64, v82, v64
	v_exp_f32_e32 v87, v69
	v_add_f32_e32 v64, v83, v64
	v_exp_f32_e32 v88, v66
	v_add_f32_e32 v64, v84, v64
	v_exp_f32_e32 v89, v67
	v_add_f32_e32 v64, v85, v64
	v_add_f32_e32 v64, v86, v64
	v_exp_f32_e32 v92, v65
	v_add_f32_e32 v64, v87, v64
	v_add_f32_e32 v64, v88, v64
	v_add_f32_e32 v64, v89, v64
	v_add_f32_e32 v64, v91, v64
	v_add_f32_e32 v64, v92, v64
	v_mov_b32_e32 v65, v64
	s_nop 1
	v_permlane32_swap_b32_e32 v64, v65
	v_cvt_pk_bf16_f32 v66, v120, v121
	v_cvt_pk_bf16_f32 v67, v122, v124
	v_cvt_pk_bf16_f32 v68, v125, v127
	v_cvt_pk_bf16_f32 v69, v123, v126
	v_cvt_pk_bf16_f32 v70, v112, v114
	v_cvt_pk_bf16_f32 v71, v115, v118
	v_cvt_pk_bf16_f32 v72, v113, v116
	v_cvt_pk_bf16_f32 v73, v117, v119
	v_cvt_pk_bf16_f32 v74, v78, v79
	v_cvt_pk_bf16_f32 v75, v76, v77
	v_cvt_pk_bf16_f32 v76, v80, v81
	v_cvt_pk_bf16_f32 v77, v82, v83
	v_cvt_pk_bf16_f32 v78, v84, v85
	v_cvt_pk_bf16_f32 v79, v86, v87
	v_cvt_pk_bf16_f32 v80, v88, v89
	v_cvt_pk_bf16_f32 v81, v91, v92
	v_permlane32_swap_b32_e32 v66, v68
	v_permlane32_swap_b32_e32 v67, v69
	v_permlane32_swap_b32_e32 v70, v72
	v_permlane32_swap_b32_e32 v71, v73
	v_permlane32_swap_b32_e32 v74, v76
	v_permlane32_swap_b32_e32 v75, v77
	v_permlane32_swap_b32_e32 v78, v80
	v_permlane32_swap_b32_e32 v79, v81
	ds_read_b64_tr_b16 v[82:83], v187 offset:0
	ds_read_b64_tr_b16 v[84:85], v187 offset:0x800
	ds_read_b64_tr_b16 v[86:87], v187 offset:0x1000
	ds_read_b64_tr_b16 v[88:89], v187 offset:0x1800
	ds_read_b64_tr_b16 v[92:93], v187 offset:0x2000
	ds_read_b64_tr_b16 v[94:95], v187 offset:0x2800
	ds_read_b64_tr_b16 v[96:97], v187 offset:0x3000
	ds_read_b64_tr_b16 v[98:99], v187 offset:0x3800
	s_waitcnt lgkmcnt(0)
	s_nop 0
	v_mfma_f32_32x32x16_bf16 v[16:31], v[66:69], v[82:85], v[16:31]
	ds_read_b64_tr_b16 v[82:83], v187 offset:0x200
	ds_read_b64_tr_b16 v[84:85], v187 offset:0xa00
	v_mfma_f32_32x32x16_bf16 v[16:31], v[70:73], v[86:89], v[16:31]
	ds_read_b64_tr_b16 v[86:87], v187 offset:0x1200
	ds_read_b64_tr_b16 v[88:89], v187 offset:0x1a00
	v_mfma_f32_32x32x16_bf16 v[16:31], v[74:77], v[92:95], v[16:31]
	ds_read_b64_tr_b16 v[92:93], v187 offset:0x2200
	ds_read_b64_tr_b16 v[94:95], v187 offset:0x2a00
	v_mfma_f32_32x32x16_bf16 v[16:31], v[78:81], v[96:99], v[16:31]
	ds_read_b64_tr_b16 v[96:97], v187 offset:0x3200
	ds_read_b64_tr_b16 v[98:99], v187 offset:0x3a00
	s_waitcnt lgkmcnt(0)
	v_mfma_f32_32x32x16_bf16 v[32:47], v[66:69], v[82:85], v[32:47]
	ds_read_b64_tr_b16 v[82:83], v187 offset:0x400
	ds_read_b64_tr_b16 v[84:85], v187 offset:0xc00
	v_mfma_f32_32x32x16_bf16 v[32:47], v[70:73], v[86:89], v[32:47]
	ds_read_b64_tr_b16 v[86:87], v187 offset:0x1400
	ds_read_b64_tr_b16 v[88:89], v187 offset:0x1c00
	v_mfma_f32_32x32x16_bf16 v[32:47], v[74:77], v[92:95], v[32:47]
	ds_read_b64_tr_b16 v[92:93], v187 offset:0x2400
	ds_read_b64_tr_b16 v[94:95], v187 offset:0x2c00
	v_mfma_f32_32x32x16_bf16 v[32:47], v[78:81], v[96:99], v[32:47]
	ds_read_b64_tr_b16 v[96:97], v187 offset:0x3400
	ds_read_b64_tr_b16 v[98:99], v187 offset:0x3c00
	s_waitcnt lgkmcnt(0)
	v_mfma_f32_32x32x16_bf16 v[48:63], v[66:69], v[82:85], v[48:63]
	ds_read_b64_tr_b16 v[82:83], v187 offset:0x600
	ds_read_b64_tr_b16 v[84:85], v187 offset:0xe00
	v_mfma_f32_32x32x16_bf16 v[48:63], v[70:73], v[86:89], v[48:63]
	ds_read_b64_tr_b16 v[86:87], v187 offset:0x1600
	ds_read_b64_tr_b16 v[88:89], v187 offset:0x1e00
	v_mfma_f32_32x32x16_bf16 v[48:63], v[74:77], v[92:95], v[48:63]
	ds_read_b64_tr_b16 v[92:93], v187 offset:0x2600
	ds_read_b64_tr_b16 v[94:95], v187 offset:0x2e00
	v_mfma_f32_32x32x16_bf16 v[48:63], v[78:81], v[96:99], v[48:63]
	ds_read_b64_tr_b16 v[96:97], v187 offset:0x3600
	ds_read_b64_tr_b16 v[98:99], v187 offset:0x3e00
	s_waitcnt lgkmcnt(0)
	v_mfma_f32_32x32x16_bf16 v[0:15], v[66:69], v[82:85], v[0:15]
	v_mfma_f32_32x32x16_bf16 v[0:15], v[70:73], v[86:89], v[0:15]
	v_mfma_f32_32x32x16_bf16 v[0:15], v[74:77], v[92:95], v[0:15]
	v_mfma_f32_32x32x16_bf16 v[0:15], v[78:81], v[96:99], v[0:15]
	s_and_saveexec_b64 s[4:5], s[6:7]
	s_cbranch_execz .LBB0_32
	v_add_f32_e32 v64, v64, v65
	v_fmac_f32_e32 v64, v237, v90
	ds_write_b32 v236, v64
	s_branch .LBB0_32
